# speedup vs baseline: 1.0174x; 1.0174x over previous
; __global__ void __launch_bounds__(512, 2) fwd_megakernel(mk::Params p) {
;     ...
;     const int tid = threadIdx.x, lane = tid & 63; const int wave = __builtin_amdgcn_readfirstlane(tid >> 6);
;     const int G = gridDim.x, bx = blockIdx.x;
;     const int vcu = (G % 8 == 0) ? (bx % 8) * (G / 8) + bx / 8 : bx;
_Z14fwd_megakernelN2mk6ParamsE:
	s_load_dwordx2 s[48:49], s[0:1], 0x98
	s_mov_b64 s[26:27], s[0:1]
	s_add_u32 s8, s26, 0x98
	s_addc_u32 s9, s27, 0
	v_and_b32_e32 v254, 0x3ff, v0
	s_waitcnt lgkmcnt(0)
	v_readfirstlane_b32 s98, v254
	s_nop 3
	s_lshr_b32 s98, s98, 8
	s_and_b32 s0, s48, 7
	s_cmp_lg_u32 s0, 0
	s_mov_b32 s0, s2
	v_writelane_b32 v255, s0, 0
	v_readfirstlane_b32 s3, v254
	s_nop 0
	v_writelane_b32 v255, s1, 1
	s_cbranch_scc1 .LBB0_2
	s_ashr_i32 s1, s2, 31
	s_lshr_b32 s1, s1, 29
	s_add_i32 s1, s2, s1
	s_and_b32 s4, s1, -8
	s_ashr_i32 s0, s48, 3
	s_sub_i32 s4, s2, s4
	s_mul_i32 s0, s0, s4
	s_ashr_i32 s1, s1, 3
	s_add_i32 s0, s0, s1
	v_writelane_b32 v255, s0, 0
	s_nop 1
	v_writelane_b32 v255, s1, 1

; __device__ __forceinline__ unsigned cvt_pk_bf16(float lo, float hi) { unsigned r; asm volatile("v_cvt_pk_bf16_f32 %0, %1, %2" : "=v"(r) : "v"(lo), "v"(hi)); return r; }
; #define GAS __attribute__((address_space(1)))
;     __device__ __forceinline__ void operator()(const f32x4 (&acc)[2][2][4][2], const Unit& u, int wr, int wc, int fr, int fq) const {
;         bf16_t* act = (u.pm >> 7) ? act1 : act0;
;         const int row0 = (u.pm & 127) * 256 + wr * 64 + fr; const int col0 = u.pn * 128 + wc * 32 + 8 * fq;
; #pragma unroll
;         for (int ai = 0; ai < 2; ++ai)
; #pragma unroll
;             for (int m = 0; m < 4; ++m) {
;                 const int row = row0 + ai * 128 + m * 16;
;                 const float rs = rsl[u.ord * 256 + wr * 64 + fr + ai * 128 + m * 16];
;                 float o[8];
; #pragma unroll
;                 for (int n = 0; n < 2; ++n)
; #pragma unroll
;                     for (int i = 0; i < 4; ++i) {
;                         const float g = acc[ai][0][m][n][i] * rs, up = acc[ai][1][m][n][i] * rs;
;                         const float e = __builtin_amdgcn_exp2f(-g * 1.4426950408889634f);
;                         o[n * 4 + i] = g * __builtin_amdgcn_rcpf(1.0f + e) * up;
;                     }
;                 u32x4 w; w.x = cvt_pk_bf16(o[0], o[1]); w.y = cvt_pk_bf16(o[2], o[3]); w.z = cvt_pk_bf16(o[4], o[5]); w.w = cvt_pk_bf16(o[6], o[7]);
;                 *(GAS u32x4*)(act + (size_t)row * DFF + col0) = w;
.LBB0_171:
	s_cmpk_lt_u32 s41, 0x80
	s_cselect_b32 s0, s97, s11
	s_cselect_b32 s1, s61, s10
	v_lshl_or_b32 v146, s40, 7, v143
	v_mov_b32_e32 v138, s1
	v_mov_b32_e32 v139, s0
	v_ashrrev_i32_e32 v147, 31, v146
	v_lshl_add_u64 v[138:139], v[146:147], 1, v[138:139]
	v_lshl_add_u32 v146, s57, 10, v142
	ds_read_b32 v152, v146
	ds_read_b32 v153, v146 offset:64
	ds_read_b32 v154, v146 offset:128
	ds_read_b32 v155, v146 offset:192
	ds_read_b32 v156, v146 offset:512
	ds_read_b32 v157, v146 offset:576
	ds_read_b32 v158, v146 offset:640
	ds_read_b32 v159, v146 offset:704
	s_lshl_b32 s0, s41, 8
	s_and_b32 s0, s0, 0x7f00
	v_add_u32_e32 v145, s0, v140
	s_andn2_b64 vcc, exec, s[6:7]
	s_waitcnt lgkmcnt(0)
	v_mul_f32_e32 v160, v124, v152
	v_mul_f32_e32 v161, v125, v152
	v_mul_f32_e32 v162, v126, v152
	v_mul_f32_e32 v163, v127, v152
	v_mul_f32_e32 v164, v116, v152
	v_mul_f32_e32 v165, v117, v152
	v_mul_f32_e32 v166, v118, v152
	v_mul_f32_e32 v167, v119, v152
	v_mul_f32_e32 v120, v120, v152
	v_mul_f32_e32 v121, v121, v152
	v_mul_f32_e32 v122, v122, v152
	v_mul_f32_e32 v123, v123, v152
	v_mul_f32_e32 v112, v112, v152
	v_mul_f32_e32 v113, v113, v152
	v_mul_f32_e32 v114, v114, v152
	v_mul_f32_e32 v115, v115, v152
	v_mul_f32_e32 v168, 0xbfb8aa3b, v160
	v_mul_f32_e32 v169, 0xbfb8aa3b, v161
	v_mul_f32_e32 v170, 0xbfb8aa3b, v162
	v_mul_f32_e32 v171, 0xbfb8aa3b, v163
	v_mul_f32_e32 v172, 0xbfb8aa3b, v164
	v_mul_f32_e32 v173, 0xbfb8aa3b, v165
	v_mul_f32_e32 v174, 0xbfb8aa3b, v166
	v_mul_f32_e32 v175, 0xbfb8aa3b, v167
	v_exp_f32_e32 v168, v168
	v_exp_f32_e32 v169, v169
	v_exp_f32_e32 v170, v170
	v_exp_f32_e32 v171, v171
	v_exp_f32_e32 v172, v172
	v_exp_f32_e32 v173, v173
	v_exp_f32_e32 v174, v174
	v_exp_f32_e32 v175, v175
	v_add_f32_e32 v168, 1.0, v168
	v_add_f32_e32 v169, 1.0, v169
	v_add_f32_e32 v170, 1.0, v170
	v_add_f32_e32 v171, 1.0, v171
	v_add_f32_e32 v172, 1.0, v172
	v_add_f32_e32 v173, 1.0, v173
	v_add_f32_e32 v174, 1.0, v174
	v_add_f32_e32 v175, 1.0, v175
	v_rcp_f32_e32 v168, v168
	v_rcp_f32_e32 v169, v169
	v_rcp_f32_e32 v170, v170
	v_rcp_f32_e32 v171, v171
	v_rcp_f32_e32 v172, v172
	v_rcp_f32_e32 v173, v173
	v_rcp_f32_e32 v174, v174
	v_rcp_f32_e32 v175, v175
	v_mul_f32_e32 v160, v160, v168
	v_mul_f32_e32 v161, v161, v169
	v_mul_f32_e32 v162, v162, v170
	v_mul_f32_e32 v163, v163, v171
	v_mul_f32_e32 v164, v164, v172
	v_mul_f32_e32 v165, v165, v173
	v_mul_f32_e32 v166, v166, v174
	v_mul_f32_e32 v167, v167, v175
	v_mul_f32_e32 v120, v120, v160
	v_mul_f32_e32 v121, v121, v161
	v_mul_f32_e32 v122, v122, v162
	v_mul_f32_e32 v123, v123, v163
	v_mul_f32_e32 v112, v112, v164
	v_mul_f32_e32 v113, v113, v165
	v_mul_f32_e32 v114, v114, v166
	v_mul_f32_e32 v115, v115, v167
	v_cvt_pk_bf16_f32 v176, v120, v121
	v_cvt_pk_bf16_f32 v177, v122, v123
	v_cvt_pk_bf16_f32 v178, v112, v113
	v_cvt_pk_bf16_f32 v179, v114, v115
	v_mad_i64_i32 v[180:181], s[38:39], v145, s53, v[138:139]
	global_store_dwordx4 v[180:181], v[176:179], off
	v_mul_f32_e32 v160, v108, v153
	v_mul_f32_e32 v161, v109, v153
	v_mul_f32_e32 v162, v110, v153
	v_mul_f32_e32 v163, v111, v153
	v_mul_f32_e32 v164, v100, v153
	v_mul_f32_e32 v165, v101, v153
	v_mul_f32_e32 v166, v102, v153
	v_mul_f32_e32 v167, v103, v153
	v_mul_f32_e32 v104, v104, v153
	v_mul_f32_e32 v105, v105, v153
	v_mul_f32_e32 v106, v106, v153
	v_mul_f32_e32 v107, v107, v153
	v_mul_f32_e32 v96, v96, v153
	v_mul_f32_e32 v97, v97, v153
	v_mul_f32_e32 v98, v98, v153
	v_mul_f32_e32 v99, v99, v153
	v_mul_f32_e32 v168, 0xbfb8aa3b, v160
	v_mul_f32_e32 v169, 0xbfb8aa3b, v161
	v_mul_f32_e32 v170, 0xbfb8aa3b, v162
	v_mul_f32_e32 v171, 0xbfb8aa3b, v163
	v_mul_f32_e32 v172, 0xbfb8aa3b, v164
	v_mul_f32_e32 v173, 0xbfb8aa3b, v165
	v_mul_f32_e32 v174, 0xbfb8aa3b, v166
	v_mul_f32_e32 v175, 0xbfb8aa3b, v167
	v_exp_f32_e32 v168, v168
	v_exp_f32_e32 v169, v169
	v_exp_f32_e32 v170, v170
	v_exp_f32_e32 v171, v171
	v_exp_f32_e32 v172, v172
	v_exp_f32_e32 v173, v173
	v_exp_f32_e32 v174, v174
	v_exp_f32_e32 v175, v175
	v_add_f32_e32 v168, 1.0, v168
	v_add_f32_e32 v169, 1.0, v169
	v_add_f32_e32 v170, 1.0, v170
	v_add_f32_e32 v171, 1.0, v171
	v_add_f32_e32 v172, 1.0, v172
	v_add_f32_e32 v173, 1.0, v173
	v_add_f32_e32 v174, 1.0, v174
	v_add_f32_e32 v175, 1.0, v175
	v_rcp_f32_e32 v168, v168
	v_rcp_f32_e32 v169, v169
	v_rcp_f32_e32 v170, v170
	v_rcp_f32_e32 v171, v171
	v_rcp_f32_e32 v172, v172
	v_rcp_f32_e32 v173, v173
	v_rcp_f32_e32 v174, v174
	v_rcp_f32_e32 v175, v175
	v_mul_f32_e32 v160, v160, v168
	v_mul_f32_e32 v161, v161, v169
	v_mul_f32_e32 v162, v162, v170
	v_mul_f32_e32 v163, v163, v171
	v_mul_f32_e32 v164, v164, v172
	v_mul_f32_e32 v165, v165, v173
	v_mul_f32_e32 v166, v166, v174
	v_mul_f32_e32 v167, v167, v175
	v_mul_f32_e32 v104, v104, v160
	v_mul_f32_e32 v105, v105, v161
	v_mul_f32_e32 v106, v106, v162
	v_mul_f32_e32 v107, v107, v163
	v_mul_f32_e32 v96, v96, v164
	v_mul_f32_e32 v97, v97, v165
	v_mul_f32_e32 v98, v98, v166
	v_mul_f32_e32 v99, v99, v167
	v_cvt_pk_bf16_f32 v184, v104, v105
	v_cvt_pk_bf16_f32 v185, v106, v107
	v_cvt_pk_bf16_f32 v186, v96, v97
	v_cvt_pk_bf16_f32 v187, v98, v99
	v_add_u32_e32 v182, 16, v145
	v_mad_i64_i32 v[188:189], s[38:39], v182, s53, v[138:139]
	global_store_dwordx4 v[188:189], v[184:187], off
	v_mul_f32_e32 v160, v92, v154
	v_mul_f32_e32 v161, v93, v154
	v_mul_f32_e32 v162, v94, v154
	v_mul_f32_e32 v163, v95, v154
	v_mul_f32_e32 v164, v84, v154
	v_mul_f32_e32 v165, v85, v154
	v_mul_f32_e32 v166, v86, v154
	v_mul_f32_e32 v167, v87, v154
	v_mul_f32_e32 v88, v88, v154
	v_mul_f32_e32 v89, v89, v154
	v_mul_f32_e32 v90, v90, v154
	v_mul_f32_e32 v91, v91, v154
	v_mul_f32_e32 v80, v80, v154
	v_mul_f32_e32 v81, v81, v154
; __device__ __forceinline__ unsigned cvt_pk_bf16(float lo, float hi) { unsigned r; asm volatile("v_cvt_pk_bf16_f32 %0, %1, %2" : "=v"(r) : "v"(lo), "v"(hi)); return r; }
; #define GAS __attribute__((address_space(1)))
;     __device__ __forceinline__ void operator()(const f32x4 (&acc)[2][2][4][2], const Unit& u, int wr, int wc, int fr, int fq) const {
;     ...
;             for (int m = 0; m < 4; ++m) {
;                 const int row = row0 + ai * 128 + m * 16;
;                 const float rs = rsl[u.ord * 256 + wr * 64 + fr + ai * 128 + m * 16];
;                 float o[8];
; #pragma unroll
;                 for (int n = 0; n < 2; ++n)
; #pragma unroll
;                     for (int i = 0; i < 4; ++i) {
;                         const float g = acc[ai][0][m][n][i] * rs, up = acc[ai][1][m][n][i] * rs;
;                         const float e = __builtin_amdgcn_exp2f(-g * 1.4426950408889634f);
;                         o[n * 4 + i] = g * __builtin_amdgcn_rcpf(1.0f + e) * up;
;                     }
;                 u32x4 w; w.x = cvt_pk_bf16(o[0], o[1]); w.y = cvt_pk_bf16(o[2], o[3]); w.z = cvt_pk_bf16(o[4], o[5]); w.w = cvt_pk_bf16(o[6], o[7]);
;                 *(GAS u32x4*)(act + (size_t)row * DFF + col0) = w;
	v_mul_f32_e32 v82, v82, v154
	v_mul_f32_e32 v83, v83, v154
	v_mul_f32_e32 v168, 0xbfb8aa3b, v160
	v_mul_f32_e32 v169, 0xbfb8aa3b, v161
	v_mul_f32_e32 v170, 0xbfb8aa3b, v162
	v_mul_f32_e32 v171, 0xbfb8aa3b, v163
	v_mul_f32_e32 v172, 0xbfb8aa3b, v164
	v_mul_f32_e32 v173, 0xbfb8aa3b, v165
	v_mul_f32_e32 v174, 0xbfb8aa3b, v166
	v_mul_f32_e32 v175, 0xbfb8aa3b, v167
	v_exp_f32_e32 v168, v168
	v_exp_f32_e32 v169, v169
	v_exp_f32_e32 v170, v170
	v_exp_f32_e32 v171, v171
	v_exp_f32_e32 v172, v172
	v_exp_f32_e32 v173, v173
	v_exp_f32_e32 v174, v174
	v_exp_f32_e32 v175, v175
	v_add_f32_e32 v168, 1.0, v168
	v_add_f32_e32 v169, 1.0, v169
	v_add_f32_e32 v170, 1.0, v170
	v_add_f32_e32 v171, 1.0, v171
	v_add_f32_e32 v172, 1.0, v172
	v_add_f32_e32 v173, 1.0, v173
	v_add_f32_e32 v174, 1.0, v174
	v_add_f32_e32 v175, 1.0, v175
	v_rcp_f32_e32 v168, v168
	v_rcp_f32_e32 v169, v169
	v_rcp_f32_e32 v170, v170
	v_rcp_f32_e32 v171, v171
	v_rcp_f32_e32 v172, v172
	v_rcp_f32_e32 v173, v173
	v_rcp_f32_e32 v174, v174
	v_rcp_f32_e32 v175, v175
	v_mul_f32_e32 v160, v160, v168
	v_mul_f32_e32 v161, v161, v169
	v_mul_f32_e32 v162, v162, v170
	v_mul_f32_e32 v163, v163, v171
	v_mul_f32_e32 v164, v164, v172
	v_mul_f32_e32 v165, v165, v173
	v_mul_f32_e32 v166, v166, v174
	v_mul_f32_e32 v167, v167, v175
	v_mul_f32_e32 v88, v88, v160
	v_mul_f32_e32 v89, v89, v161
	v_mul_f32_e32 v90, v90, v162
	v_mul_f32_e32 v91, v91, v163
	v_mul_f32_e32 v80, v80, v164
	v_mul_f32_e32 v81, v81, v165
	v_mul_f32_e32 v82, v82, v166
	v_mul_f32_e32 v83, v83, v167
	v_cvt_pk_bf16_f32 v176, v88, v89
	v_cvt_pk_bf16_f32 v177, v90, v91
	v_cvt_pk_bf16_f32 v178, v80, v81
	v_cvt_pk_bf16_f32 v179, v82, v83
	v_add_u32_e32 v182, 32, v145
	v_mad_i64_i32 v[180:181], s[38:39], v182, s53, v[138:139]
	global_store_dwordx4 v[180:181], v[176:179], off
	v_mul_f32_e32 v160, v76, v155
	v_mul_f32_e32 v161, v77, v155
	v_mul_f32_e32 v162, v78, v155
	v_mul_f32_e32 v163, v79, v155
	v_mul_f32_e32 v164, v68, v155
	v_mul_f32_e32 v165, v69, v155
	v_mul_f32_e32 v166, v70, v155
	v_mul_f32_e32 v167, v71, v155
	v_mul_f32_e32 v72, v72, v155
	v_mul_f32_e32 v73, v73, v155
	v_mul_f32_e32 v74, v74, v155
	v_mul_f32_e32 v75, v75, v155
	v_mul_f32_e32 v64, v64, v155
	v_mul_f32_e32 v65, v65, v155
	v_mul_f32_e32 v66, v66, v155
	v_mul_f32_e32 v67, v67, v155
	v_mul_f32_e32 v168, 0xbfb8aa3b, v160
	v_mul_f32_e32 v169, 0xbfb8aa3b, v161
	v_mul_f32_e32 v170, 0xbfb8aa3b, v162
	v_mul_f32_e32 v171, 0xbfb8aa3b, v163
	v_mul_f32_e32 v172, 0xbfb8aa3b, v164
	v_mul_f32_e32 v173, 0xbfb8aa3b, v165
	v_mul_f32_e32 v174, 0xbfb8aa3b, v166
	v_mul_f32_e32 v175, 0xbfb8aa3b, v167
	v_exp_f32_e32 v168, v168
	v_exp_f32_e32 v169, v169
	v_exp_f32_e32 v170, v170
	v_exp_f32_e32 v171, v171
	v_exp_f32_e32 v172, v172
	v_exp_f32_e32 v173, v173
	v_exp_f32_e32 v174, v174
	v_exp_f32_e32 v175, v175
	v_add_f32_e32 v168, 1.0, v168
	v_add_f32_e32 v169, 1.0, v169
	v_add_f32_e32 v170, 1.0, v170
	v_add_f32_e32 v171, 1.0, v171
	v_add_f32_e32 v172, 1.0, v172
	v_add_f32_e32 v173, 1.0, v173
	v_add_f32_e32 v174, 1.0, v174
	v_add_f32_e32 v175, 1.0, v175
	v_rcp_f32_e32 v168, v168
	v_rcp_f32_e32 v169, v169
	v_rcp_f32_e32 v170, v170
	v_rcp_f32_e32 v171, v171
	v_rcp_f32_e32 v172, v172
	v_rcp_f32_e32 v173, v173
	v_rcp_f32_e32 v174, v174
	v_rcp_f32_e32 v175, v175
	v_mul_f32_e32 v160, v160, v168
	v_mul_f32_e32 v161, v161, v169
	v_mul_f32_e32 v162, v162, v170
	v_mul_f32_e32 v163, v163, v171
	v_mul_f32_e32 v164, v164, v172
	v_mul_f32_e32 v165, v165, v173
	v_mul_f32_e32 v166, v166, v174
	v_mul_f32_e32 v167, v167, v175
	v_mul_f32_e32 v72, v72, v160
	v_mul_f32_e32 v73, v73, v161
	v_mul_f32_e32 v74, v74, v162
	v_mul_f32_e32 v75, v75, v163
	v_mul_f32_e32 v64, v64, v164
	v_mul_f32_e32 v65, v65, v165
	v_mul_f32_e32 v66, v66, v166
	v_mul_f32_e32 v67, v67, v167
	v_cvt_pk_bf16_f32 v184, v72, v73
	v_cvt_pk_bf16_f32 v185, v74, v75
	v_cvt_pk_bf16_f32 v186, v64, v65
	v_cvt_pk_bf16_f32 v187, v66, v67
	v_add_u32_e32 v182, 48, v145
	v_mad_i64_i32 v[188:189], s[38:39], v182, s53, v[138:139]
	global_store_dwordx4 v[188:189], v[184:187], off
	v_mul_f32_e32 v160, v60, v156
	v_mul_f32_e32 v161, v61, v156
	v_mul_f32_e32 v162, v62, v156
	v_mul_f32_e32 v163, v63, v156
	v_mul_f32_e32 v164, v52, v156
	v_mul_f32_e32 v165, v53, v156
	v_mul_f32_e32 v166, v54, v156
	v_mul_f32_e32 v167, v55, v156
	v_mul_f32_e32 v56, v56, v156
	v_mul_f32_e32 v57, v57, v156
	v_mul_f32_e32 v58, v58, v156
	v_mul_f32_e32 v59, v59, v156
	v_mul_f32_e32 v48, v48, v156
	v_mul_f32_e32 v49, v49, v156
	v_mul_f32_e32 v50, v50, v156
	v_mul_f32_e32 v51, v51, v156
	v_mul_f32_e32 v168, 0xbfb8aa3b, v160
	v_mul_f32_e32 v169, 0xbfb8aa3b, v161
	v_mul_f32_e32 v170, 0xbfb8aa3b, v162
	v_mul_f32_e32 v171, 0xbfb8aa3b, v163
	v_mul_f32_e32 v172, 0xbfb8aa3b, v164
	v_mul_f32_e32 v173, 0xbfb8aa3b, v165
	v_mul_f32_e32 v174, 0xbfb8aa3b, v166
	v_mul_f32_e32 v175, 0xbfb8aa3b, v167
	v_exp_f32_e32 v168, v168
	v_exp_f32_e32 v169, v169
	v_exp_f32_e32 v170, v170
	v_exp_f32_e32 v171, v171
	v_exp_f32_e32 v172, v172
	v_exp_f32_e32 v173, v173
	v_exp_f32_e32 v174, v174
	v_exp_f32_e32 v175, v175
	v_add_f32_e32 v168, 1.0, v168
	v_add_f32_e32 v169, 1.0, v169
	v_add_f32_e32 v170, 1.0, v170
	v_add_f32_e32 v171, 1.0, v171
	v_add_f32_e32 v172, 1.0, v172
	v_add_f32_e32 v173, 1.0, v173
	v_add_f32_e32 v174, 1.0, v174
	v_add_f32_e32 v175, 1.0, v175
	v_rcp_f32_e32 v168, v168
	v_rcp_f32_e32 v169, v169
	v_rcp_f32_e32 v170, v170
	v_rcp_f32_e32 v171, v171
	v_rcp_f32_e32 v172, v172
	v_rcp_f32_e32 v173, v173
	v_rcp_f32_e32 v174, v174
	v_rcp_f32_e32 v175, v175
	v_mul_f32_e32 v160, v160, v168
	v_mul_f32_e32 v161, v161, v169
	v_mul_f32_e32 v162, v162, v170
	v_mul_f32_e32 v163, v163, v171
	v_mul_f32_e32 v164, v164, v172
; __device__ __forceinline__ unsigned cvt_pk_bf16(float lo, float hi) { unsigned r; asm volatile("v_cvt_pk_bf16_f32 %0, %1, %2" : "=v"(r) : "v"(lo), "v"(hi)); return r; }
; #define GAS __attribute__((address_space(1)))
;     __device__ __forceinline__ void operator()(const f32x4 (&acc)[2][2][4][2], const Unit& u, int wr, int wc, int fr, int fq) const {
;     ...
;             for (int m = 0; m < 4; ++m) {
;                 const int row = row0 + ai * 128 + m * 16;
;                 const float rs = rsl[u.ord * 256 + wr * 64 + fr + ai * 128 + m * 16];
;                 float o[8];
; #pragma unroll
;                 for (int n = 0; n < 2; ++n)
; #pragma unroll
;                     for (int i = 0; i < 4; ++i) {
;                         const float g = acc[ai][0][m][n][i] * rs, up = acc[ai][1][m][n][i] * rs;
;                         const float e = __builtin_amdgcn_exp2f(-g * 1.4426950408889634f);
;                         o[n * 4 + i] = g * __builtin_amdgcn_rcpf(1.0f + e) * up;
;                     }
;                 u32x4 w; w.x = cvt_pk_bf16(o[0], o[1]); w.y = cvt_pk_bf16(o[2], o[3]); w.z = cvt_pk_bf16(o[4], o[5]); w.w = cvt_pk_bf16(o[6], o[7]);
;                 *(GAS u32x4*)(act + (size_t)row * DFF + col0) = w;
	v_mul_f32_e32 v165, v165, v173
	v_mul_f32_e32 v166, v166, v174
	v_mul_f32_e32 v167, v167, v175
	v_mul_f32_e32 v56, v56, v160
	v_mul_f32_e32 v57, v57, v161
	v_mul_f32_e32 v58, v58, v162
	v_mul_f32_e32 v59, v59, v163
	v_mul_f32_e32 v48, v48, v164
	v_mul_f32_e32 v49, v49, v165
	v_mul_f32_e32 v50, v50, v166
	v_mul_f32_e32 v51, v51, v167
	v_cvt_pk_bf16_f32 v176, v56, v57
	v_cvt_pk_bf16_f32 v177, v58, v59
	v_cvt_pk_bf16_f32 v178, v48, v49
	v_cvt_pk_bf16_f32 v179, v50, v51
	v_add_u32_e32 v182, 0x80, v145
	v_mad_i64_i32 v[180:181], s[38:39], v182, s53, v[138:139]
	global_store_dwordx4 v[180:181], v[176:179], off
	v_mul_f32_e32 v160, v44, v157
	v_mul_f32_e32 v161, v45, v157
	v_mul_f32_e32 v162, v46, v157
	v_mul_f32_e32 v163, v47, v157
	v_mul_f32_e32 v164, v36, v157
	v_mul_f32_e32 v165, v37, v157
	v_mul_f32_e32 v166, v38, v157
	v_mul_f32_e32 v167, v39, v157
	v_mul_f32_e32 v40, v40, v157
	v_mul_f32_e32 v41, v41, v157
	v_mul_f32_e32 v42, v42, v157
	v_mul_f32_e32 v43, v43, v157
	v_mul_f32_e32 v32, v32, v157
	v_mul_f32_e32 v33, v33, v157
	v_mul_f32_e32 v34, v34, v157
	v_mul_f32_e32 v35, v35, v157
	v_mul_f32_e32 v168, 0xbfb8aa3b, v160
	v_mul_f32_e32 v169, 0xbfb8aa3b, v161
	v_mul_f32_e32 v170, 0xbfb8aa3b, v162
	v_mul_f32_e32 v171, 0xbfb8aa3b, v163
	v_mul_f32_e32 v172, 0xbfb8aa3b, v164
	v_mul_f32_e32 v173, 0xbfb8aa3b, v165
	v_mul_f32_e32 v174, 0xbfb8aa3b, v166
	v_mul_f32_e32 v175, 0xbfb8aa3b, v167
	v_exp_f32_e32 v168, v168
	v_exp_f32_e32 v169, v169
	v_exp_f32_e32 v170, v170
	v_exp_f32_e32 v171, v171
	v_exp_f32_e32 v172, v172
	v_exp_f32_e32 v173, v173
	v_exp_f32_e32 v174, v174
	v_exp_f32_e32 v175, v175
	v_add_f32_e32 v168, 1.0, v168
	v_add_f32_e32 v169, 1.0, v169
	v_add_f32_e32 v170, 1.0, v170
	v_add_f32_e32 v171, 1.0, v171
	v_add_f32_e32 v172, 1.0, v172
	v_add_f32_e32 v173, 1.0, v173
	v_add_f32_e32 v174, 1.0, v174
	v_add_f32_e32 v175, 1.0, v175
	v_rcp_f32_e32 v168, v168
	v_rcp_f32_e32 v169, v169
	v_rcp_f32_e32 v170, v170
	v_rcp_f32_e32 v171, v171
	v_rcp_f32_e32 v172, v172
	v_rcp_f32_e32 v173, v173
	v_rcp_f32_e32 v174, v174
	v_rcp_f32_e32 v175, v175
	v_mul_f32_e32 v160, v160, v168
	v_mul_f32_e32 v161, v161, v169
	v_mul_f32_e32 v162, v162, v170
	v_mul_f32_e32 v163, v163, v171
	v_mul_f32_e32 v164, v164, v172
	v_mul_f32_e32 v165, v165, v173
	v_mul_f32_e32 v166, v166, v174
	v_mul_f32_e32 v167, v167, v175
	v_mul_f32_e32 v40, v40, v160
	v_mul_f32_e32 v41, v41, v161
	v_mul_f32_e32 v42, v42, v162
	v_mul_f32_e32 v43, v43, v163
	v_mul_f32_e32 v32, v32, v164
	v_mul_f32_e32 v33, v33, v165
	v_mul_f32_e32 v34, v34, v166
	v_mul_f32_e32 v35, v35, v167
	v_cvt_pk_bf16_f32 v184, v40, v41
	v_cvt_pk_bf16_f32 v185, v42, v43
	v_cvt_pk_bf16_f32 v186, v32, v33
	v_cvt_pk_bf16_f32 v187, v34, v35
	v_add_u32_e32 v182, 0x90, v145
	v_mad_i64_i32 v[188:189], s[38:39], v182, s53, v[138:139]
	global_store_dwordx4 v[188:189], v[184:187], off
	v_mul_f32_e32 v160, v28, v158
	v_mul_f32_e32 v161, v29, v158
	v_mul_f32_e32 v162, v30, v158
	v_mul_f32_e32 v163, v31, v158
	v_mul_f32_e32 v164, v20, v158
	v_mul_f32_e32 v165, v21, v158
	v_mul_f32_e32 v166, v22, v158
	v_mul_f32_e32 v167, v23, v158
	v_mul_f32_e32 v24, v24, v158
	v_mul_f32_e32 v25, v25, v158
	v_mul_f32_e32 v26, v26, v158
	v_mul_f32_e32 v27, v27, v158
	v_mul_f32_e32 v16, v16, v158
	v_mul_f32_e32 v17, v17, v158
	v_mul_f32_e32 v18, v18, v158
	v_mul_f32_e32 v19, v19, v158
	v_mul_f32_e32 v168, 0xbfb8aa3b, v160
	v_mul_f32_e32 v169, 0xbfb8aa3b, v161
	v_mul_f32_e32 v170, 0xbfb8aa3b, v162
	v_mul_f32_e32 v171, 0xbfb8aa3b, v163
	v_mul_f32_e32 v172, 0xbfb8aa3b, v164
	v_mul_f32_e32 v173, 0xbfb8aa3b, v165
	v_mul_f32_e32 v174, 0xbfb8aa3b, v166
	v_mul_f32_e32 v175, 0xbfb8aa3b, v167
	v_exp_f32_e32 v168, v168
	v_exp_f32_e32 v169, v169
	v_exp_f32_e32 v170, v170
; __device__ __forceinline__ unsigned cvt_pk_bf16(float lo, float hi) { unsigned r; asm volatile("v_cvt_pk_bf16_f32 %0, %1, %2" : "=v"(r) : "v"(lo), "v"(hi)); return r; }
; #define GAS __attribute__((address_space(1)))
;     __device__ __forceinline__ void operator()(const f32x4 (&acc)[2][2][4][2], const Unit& u, int wr, int wc, int fr, int fq) const {
;     ...
;             for (int m = 0; m < 4; ++m) {
;                 const int row = row0 + ai * 128 + m * 16;
;                 const float rs = rsl[u.ord * 256 + wr * 64 + fr + ai * 128 + m * 16];
;                 float o[8];
; #pragma unroll
;                 for (int n = 0; n < 2; ++n)
; #pragma unroll
;                     for (int i = 0; i < 4; ++i) {
;                         const float g = acc[ai][0][m][n][i] * rs, up = acc[ai][1][m][n][i] * rs;
;                         const float e = __builtin_amdgcn_exp2f(-g * 1.4426950408889634f);
;                         o[n * 4 + i] = g * __builtin_amdgcn_rcpf(1.0f + e) * up;
;                     }
;                 u32x4 w; w.x = cvt_pk_bf16(o[0], o[1]); w.y = cvt_pk_bf16(o[2], o[3]); w.z = cvt_pk_bf16(o[4], o[5]); w.w = cvt_pk_bf16(o[6], o[7]);
;                 *(GAS u32x4*)(act + (size_t)row * DFF + col0) = w;
;             }
;     }
	v_exp_f32_e32 v171, v171
	v_exp_f32_e32 v172, v172
	v_exp_f32_e32 v173, v173
	v_exp_f32_e32 v174, v174
	v_exp_f32_e32 v175, v175
	v_add_f32_e32 v168, 1.0, v168
	v_add_f32_e32 v169, 1.0, v169
	v_add_f32_e32 v170, 1.0, v170
	v_add_f32_e32 v171, 1.0, v171
	v_add_f32_e32 v172, 1.0, v172
	v_add_f32_e32 v173, 1.0, v173
	v_add_f32_e32 v174, 1.0, v174
	v_add_f32_e32 v175, 1.0, v175
	v_rcp_f32_e32 v168, v168
	v_rcp_f32_e32 v169, v169
	v_rcp_f32_e32 v170, v170
	v_rcp_f32_e32 v171, v171
	v_rcp_f32_e32 v172, v172
	v_rcp_f32_e32 v173, v173
	v_rcp_f32_e32 v174, v174
	v_rcp_f32_e32 v175, v175
	v_mul_f32_e32 v160, v160, v168
	v_mul_f32_e32 v161, v161, v169
	v_mul_f32_e32 v162, v162, v170
	v_mul_f32_e32 v163, v163, v171
	v_mul_f32_e32 v164, v164, v172
	v_mul_f32_e32 v165, v165, v173
	v_mul_f32_e32 v166, v166, v174
	v_mul_f32_e32 v167, v167, v175
	v_mul_f32_e32 v24, v24, v160
	v_mul_f32_e32 v25, v25, v161
	v_mul_f32_e32 v26, v26, v162
	v_mul_f32_e32 v27, v27, v163
	v_mul_f32_e32 v16, v16, v164
	v_mul_f32_e32 v17, v17, v165
	v_mul_f32_e32 v18, v18, v166
	v_mul_f32_e32 v19, v19, v167
	v_cvt_pk_bf16_f32 v176, v24, v25
	v_cvt_pk_bf16_f32 v177, v26, v27
	v_cvt_pk_bf16_f32 v178, v16, v17
	v_cvt_pk_bf16_f32 v179, v18, v19
	v_add_u32_e32 v182, 0xa0, v145
	v_mad_i64_i32 v[180:181], s[38:39], v182, s53, v[138:139]
	global_store_dwordx4 v[180:181], v[176:179], off
	v_mul_f32_e32 v160, v12, v159
	v_mul_f32_e32 v161, v13, v159
	v_mul_f32_e32 v162, v14, v159
	v_mul_f32_e32 v163, v15, v159
	v_mul_f32_e32 v164, v4, v159
	v_mul_f32_e32 v165, v5, v159
	v_mul_f32_e32 v166, v6, v159
	v_mul_f32_e32 v167, v7, v159
	v_mul_f32_e32 v8, v8, v159
	v_mul_f32_e32 v9, v9, v159
	v_mul_f32_e32 v10, v10, v159
	v_mul_f32_e32 v11, v11, v159
	v_mul_f32_e32 v0, v0, v159
	v_mul_f32_e32 v1, v1, v159
	v_mul_f32_e32 v2, v2, v159
	v_mul_f32_e32 v3, v3, v159
	v_mul_f32_e32 v168, 0xbfb8aa3b, v160
	v_mul_f32_e32 v169, 0xbfb8aa3b, v161
	v_mul_f32_e32 v170, 0xbfb8aa3b, v162
	v_mul_f32_e32 v171, 0xbfb8aa3b, v163
	v_mul_f32_e32 v172, 0xbfb8aa3b, v164
	v_mul_f32_e32 v173, 0xbfb8aa3b, v165
	v_mul_f32_e32 v174, 0xbfb8aa3b, v166
	v_mul_f32_e32 v175, 0xbfb8aa3b, v167
	v_exp_f32_e32 v168, v168
	v_exp_f32_e32 v169, v169
	v_exp_f32_e32 v170, v170
	v_exp_f32_e32 v171, v171
	v_exp_f32_e32 v172, v172
	v_exp_f32_e32 v173, v173
	v_exp_f32_e32 v174, v174
	v_exp_f32_e32 v175, v175
	v_add_f32_e32 v168, 1.0, v168
	v_add_f32_e32 v169, 1.0, v169
	v_add_f32_e32 v170, 1.0, v170
	v_add_f32_e32 v171, 1.0, v171
	v_add_f32_e32 v172, 1.0, v172
	v_add_f32_e32 v173, 1.0, v173
	v_add_f32_e32 v174, 1.0, v174
	v_add_f32_e32 v175, 1.0, v175
	v_rcp_f32_e32 v168, v168
	v_rcp_f32_e32 v169, v169
	v_rcp_f32_e32 v170, v170
	v_rcp_f32_e32 v171, v171
	v_rcp_f32_e32 v172, v172
	v_rcp_f32_e32 v173, v173
	v_rcp_f32_e32 v174, v174
	v_rcp_f32_e32 v175, v175
	v_mul_f32_e32 v160, v160, v168
	v_mul_f32_e32 v161, v161, v169
	v_mul_f32_e32 v162, v162, v170
	v_mul_f32_e32 v163, v163, v171
	v_mul_f32_e32 v164, v164, v172
	v_mul_f32_e32 v165, v165, v173
	v_mul_f32_e32 v166, v166, v174
	v_mul_f32_e32 v167, v167, v175
	v_mul_f32_e32 v8, v8, v160
	v_mul_f32_e32 v9, v9, v161
	v_mul_f32_e32 v10, v10, v162
	v_mul_f32_e32 v11, v11, v163
	v_mul_f32_e32 v0, v0, v164
	v_mul_f32_e32 v1, v1, v165
	v_mul_f32_e32 v2, v2, v166
	v_mul_f32_e32 v3, v3, v167
	v_cvt_pk_bf16_f32 v184, v8, v9
	v_cvt_pk_bf16_f32 v185, v10, v11
	v_cvt_pk_bf16_f32 v186, v0, v1
	v_cvt_pk_bf16_f32 v187, v2, v3
	v_add_u32_e32 v182, 0xb0, v145
	v_mad_i64_i32 v[188:189], s[38:39], v182, s53, v[138:139]
	global_store_dwordx4 v[188:189], v[184:187], off
	s_mov_b64 s[38:39], -1
	s_cbranch_vccnz .LBB0_164
	s_andn2_b64 vcc, exec, s[18:19]
	s_cbranch_vccnz .LBB0_163
	s_barrier
	s_branch .LBB0_163

; #define LAS __attribute__((address_space(3)))
; #define GAS __attribute__((address_space(1)))
; __device__ __forceinline__ void attn_unit(LAS unsigned char* lds, bf16_t* Qm, const bf16_t* __restrict__ Kb, const bf16_t* __restrict__ Vt,
;                                           int b, int h, int qb, int lgS, float lam, float oscale, const float* __restrict__ subg, float* stash) {
;     ...
;         {
;             kreg = *(const GAS u32x4*)kg; vreg0 = *(const GAS u32x4*)vg0; vreg1 = *(const GAS u32x4*)vg1;
;             const u32x4 k1 = *(const GAS u32x4*)(kg + (size_t)64 * 512), k2 = *(const GAS u32x4*)(kg + (size_t)2 * 64 * 512), v10 = *(const GAS u32x4*)(vg0 + 64), v11 = *(const GAS u32x4*)(vg1 + 64);
;             *(LAS u32x4*)(lds + kw) = kreg; *(LAS u32x4*)(lds + vw0) = vreg0; *(LAS u32x4*)(lds + vw1) = vreg1;
;             *(LAS u32x4*)(lds + KBUF + kw) = k1; *(LAS u32x4*)(lds + VBUF + vw0) = v10; *(LAS u32x4*)(lds + VBUF + vw1) = v11;
;             *(LAS u32x4*)(lds + 2 * KBUF + kw) = k2;
;             kreg = *(const GAS u32x4*)(kg + (size_t)3 * 64 * 512); vreg0 = *(const GAS u32x4*)(vg0 + 2 * 64); vreg1 = *(const GAS u32x4*)(vg1 + 2 * 64);
;         }
;         __syncthreads();
;         u32x4 pk[4]; bf16x8 kf[8]; bf16x8 vfa[4], vfb[4];
;         {
;             f32x16 p0, p1;
;             ATT_KRD(0, 0, 4);
;             ATT_QK(p0, p1);
;             float mx;
;             {
;                 float a_ = ATT_MX3(p0[0], p0[1], p1[0]), b_ = ATT_MX3(p0[2], p0[3], p1[1]); a_ = ATT_MX3(a_, p1[2], p1[3]);
; #pragma unroll
;                 for (int r = 4; r < 16; r += 4) { a_ = ATT_MX3(a_, p0[r], p0[r + 1]); b_ = ATT_MX3(b_, p0[r + 2], p0[r + 3]); a_ = ATT_MX3(a_, p1[r], p1[r + 1]); b_ = ATT_MX3(b_, p1[r + 2], p1[r + 3]); }
;                 const float m_ = __builtin_fmaxf(a_, b_);
;                 auto rr_ = __builtin_amdgcn_permlane32_swap(__float_as_uint(m_), __float_as_uint(m_), false, false);
;                 mx = __builtin_fmaxf(__uint_as_float(rr_[0]), __uint_as_float(rr_[1]));
;             }
;             mhat = mx;
; #pragma unroll
;             for (int r = 0; r < 16; ++r) negm[r] = -mx;
;             float sum = 0.f;
; #pragma unroll
;             for (int r = 0; r < 16; ++r) { p0[r] = __builtin_amdgcn_exp2f(p0[r] - mx); p1[r] = __builtin_amdgcn_exp2f(p1[r] - mx); sum += p0[r] + p1[r]; }
;             lrun = sum;
; #pragma unroll
.LBB0_334:
	s_or_b32 s90, s25, s5
	s_lshl_b64 s[28:29], s[90:91], 1
	v_lshl_add_u64 v[12:13], v[228:229], 0, s[28:29]
	v_add_co_u32_e32 v4, vcc, 0x10000, v12
	v_lshl_add_u64 v[14:15], v[226:227], 0, s[28:29]
	s_nop 0
	v_addc_co_u32_e32 v5, vcc, 0, v13, vcc
	global_load_dwordx4 v[0:3], v[12:13], off
	s_nop 0
	global_load_dwordx4 v[4:7], v[4:5], off
	v_add_co_u32_e32 v8, vcc, 0x20000, v12
	v_add_u32_e32 v16, 0, v234
	s_nop 0
	v_addc_co_u32_e32 v9, vcc, 0, v13, vcc
	global_load_dwordx4 v[8:11], v[8:9], off
	s_nop 0
	global_load_dwordx4 v[136:139], v[14:15], off
	global_load_dwordx4 v[140:143], v[14:15], off offset:32
	global_load_dwordx4 v[144:147], v[14:15], off offset:64
	global_load_dwordx4 v[148:151], v[14:15], off offset:96
	v_add_co_u32_e32 v12, vcc, 0x30000, v12
	s_waitcnt vmcnt(8)
	v_mov_b64_e32 v[170:171], v[130:131]
	v_addc_co_u32_e32 v13, vcc, 0, v13, vcc
	global_load_dwordx4 v[152:155], v[12:13], off
	s_waitcnt vmcnt(8)
	v_mov_b64_e32 v[178:179], v[134:135]
	v_lshl_add_u64 v[238:239], v[236:237], 0, s[28:29]
	s_mov_b32 s56, 0x9000
	s_movk_i32 s50, 0x2100
	s_movk_i32 s29, 0x4200
	s_movk_i32 s25, 0x4800
	s_movk_i32 s90, 0xc0
	v_mov_b64_e32 v[168:169], v[128:129]
	v_mov_b64_e32 v[176:177], v[132:133]
	s_mov_b32 s28, 0
	s_mov_b32 s57, 0
	s_mov_b32 s60, 0
	s_waitcnt vmcnt(7)
	ds_write_b128 v248, v[0:3]
	ds_write_b128 v16, v[112:115] offset:25344
	ds_write_b128 v16, v[116:119] offset:34560
	s_waitcnt vmcnt(6)
	ds_write_b128 v248, v[4:7] offset:8448
	ds_write_b128 v16, v[120:123] offset:43776
	ds_write_b128 v16, v[124:127] offset:52992
	s_waitcnt vmcnt(5)
	ds_write_b128 v248, v[8:11] offset:16896
	s_waitcnt lgkmcnt(0)
	s_barrier
	ds_read_b128 v[0:3], v235
	ds_read_b128 v[18:21], v235 offset:512
	s_waitcnt vmcnt(4) lgkmcnt(1)
	v_mfma_f32_32x32x16_bf16 v[2:17], v[0:3], v[136:139], 0
	ds_read_b128 v[34:37], v235 offset:2112
	ds_read_b128 v[38:41], v235 offset:2624
	v_mov_b32_e32 v0, 0
	v_mov_b32_e32 v51, v0
	v_mov_b32_e32 v52, v0
	v_mov_b32_e32 v53, v0
	v_mov_b32_e32 v54, v0
	v_mov_b32_e32 v55, v0
	s_waitcnt lgkmcnt(2)
	v_mfma_f32_32x32x16_bf16 v[18:33], v[18:21], v[136:139], 0
	v_mov_b32_e32 v56, v0
	v_mov_b32_e32 v57, v0
	v_mov_b32_e32 v58, v0
	v_mov_b32_e32 v59, v0
	v_mov_b32_e32 v60, v0
	v_mov_b32_e32 v61, v0
	v_mov_b32_e32 v62, v0
	s_waitcnt vmcnt(3) lgkmcnt(1)
	v_mfma_f32_32x32x16_bf16 v[2:17], v[34:37], v[140:143], v[2:17]
	v_mov_b32_e32 v63, v0
	s_waitcnt lgkmcnt(0)
	v_mfma_f32_32x32x16_bf16 v[18:33], v[38:41], v[140:143], v[18:33]
	ds_read_b128 v[34:37], v235 offset:4224
	ds_read_b128 v[38:41], v235 offset:4736
	s_waitcnt vmcnt(2) lgkmcnt(1)
	v_mfma_f32_32x32x16_bf16 v[2:17], v[34:37], v[144:147], v[2:17]
	ds_read_b128 v[34:37], v235 offset:6336
	s_waitcnt lgkmcnt(1)
	v_mfma_f32_32x32x16_bf16 v[18:33], v[38:41], v[144:147], v[18:33]
	ds_read_b128 v[38:41], v235 offset:6848
	ds_read_b128 v[156:159], v235 offset:8448
	ds_read_b128 v[160:163], v235 offset:8960
	ds_read_b128 v[204:207], v235 offset:10560
	ds_read_b128 v[208:211], v235 offset:11072
	ds_read_b128 v[212:215], v235 offset:12672
	ds_read_b128 v[216:219], v235 offset:13184
	ds_read_b128 v[222:225], v235 offset:14784
	ds_read_b128 v[240:243], v235 offset:15296
	ds_read_b128 v[196:199], v220 offset:25344
	ds_read_b128 v[192:195], v220 offset:29952
	ds_read_b128 v[188:191], v220 offset:34560
	ds_read_b128 v[184:187], v220 offset:39168
	s_waitcnt lgkmcnt(0)
	s_barrier
	s_waitcnt vmcnt(1)
	v_mfma_f32_32x32x16_bf16 v[2:17], v[34:37], v[148:151], v[2:17]
	v_mfma_f32_32x32x16_bf16 v[18:33], v[38:41], v[148:151], v[18:33]
	s_nop 10
	v_max_f32_e32 v1, v3, v3
	v_max_f32_e32 v34, v2, v2
	v_max_f32_e32 v1, v34, v1
	v_max3_f32 v35, v4, v5, v19
	v_max3_f32 v1, v1, v18, v20
	v_max3_f32 v34, v35, v8, v9
	v_max3_f32 v1, v1, v21, v6
	v_max3_f32 v34, v34, v24, v25
	v_max3_f32 v1, v1, v7, v22
	v_max3_f32 v34, v34, v12, v13
	v_max3_f32 v1, v1, v23, v10
	v_max3_f32 v34, v34, v28, v29
	v_max3_f32 v1, v1, v11, v26
	v_max3_f32 v34, v34, v16, v17
	v_max3_f32 v1, v1, v27, v14
	v_max3_f32 v34, v34, v32, v33
	v_max3_f32 v1, v1, v15, v30
	v_max3_f32 v1, v1, v31, v34
	v_mov_b32_e32 v34, v1
	s_nop 1
	v_permlane32_swap_b32_e32 v1, v34
	v_max_f32_e32 v34, v34, v34
	v_max_f32_e32 v1, v1, v1
	v_max_f32_e32 v250, v1, v34
	v_sub_f32_e32 v1, v26, v250
	v_sub_f32_e32 v26, v27, v250
	v_sub_f32_e32 v27, v28, v250
	v_sub_f32_e32 v28, v29, v250
	v_sub_f32_e32 v29, v30, v250
	v_sub_f32_e32 v30, v31, v250
	v_sub_f32_e32 v31, v32, v250
	v_sub_f32_e32 v41, v18, v250
	v_sub_f32_e32 v42, v19, v250
	v_sub_f32_e32 v47, v2, v250
	v_sub_f32_e32 v32, v33, v250
	v_sub_f32_e32 v36, v13, v250
	v_sub_f32_e32 v48, v3, v250
	v_sub_f32_e32 v49, v4, v250
	v_exp_f32_e32 v3, v1
	v_exp_f32_e32 v4, v28
	v_exp_f32_e32 v13, v31
	v_exp_f32_e32 v1, v41
	v_exp_f32_e32 v28, v42
	v_exp_f32_e32 v31, v47
	v_sub_f32_e32 v33, v10, v250
	v_sub_f32_e32 v35, v12, v250
	v_sub_f32_e32 v43, v20, v250
	v_exp_f32_e32 v12, v32
	v_exp_f32_e32 v32, v48
	v_sub_f32_e32 v34, v11, v250
	v_sub_f32_e32 v38, v15, v250
	v_sub_f32_e32 v44, v21, v250
	v_sub_f32_e32 v50, v5, v250
	v_exp_f32_e32 v11, v29
	v_exp_f32_e32 v15, v33
	v_exp_f32_e32 v29, v43
	v_exp_f32_e32 v33, v49
	v_sub_f32_e32 v37, v14, v250
	v_sub_f32_e32 v22, v22, v250
	v_sub_f32_e32 v45, v23, v250
	v_exp_f32_e32 v10, v30
	v_exp_f32_e32 v14, v34
	v_exp_f32_e32 v30, v44
	v_exp_f32_e32 v34, v50
	v_sub_f32_e32 v6, v6, v250
	v_exp_f32_e32 v5, v27
	v_exp_f32_e32 v23, v22
	v_exp_f32_e32 v22, v45
	v_cvt_pk_bf16_f32 v172, v1, v28
	v_exp_f32_e32 v27, v6
	v_sub_f32_e32 v6, v7, v250
	v_add_f32_e32 v1, v1, v31
	v_exp_f32_e32 v2, v26
	v_exp_f32_e32 v26, v6
	v_sub_f32_e32 v6, v8, v250
	v_add_f32_e32 v1, 0, v1
; #define LAS __attribute__((address_space(3)))
; #define GAS __attribute__((address_space(1)))
; __device__ __forceinline__ unsigned cvtpk_s(float lo, float hi) { f32x2_t v = {lo, hi}; bf16x2_t b = __builtin_convertvector(v, bf16x2_t); return __builtin_bit_cast(unsigned, b); }
; #define ATT_KRD(KOFF, DLO, DHI) do { _Pragma("unroll") for (int d0 = (DLO); d0 < (DHI); ++d0) { kf[2 * d0] = *(const LAS bf16x8*)(lds + (KOFF) + kr + 2 * d0 * KCH); kf[2 * d0 + 1] = *(const LAS bf16x8*)(lds + (KOFF) + kr + 2 * d0 * KCH + 512); } } while (0)
; #define ATT_SB() __builtin_amdgcn_sched_barrier(0)
; __device__ __forceinline__ void attn_unit(LAS unsigned char* lds, bf16_t* Qm, const bf16_t* __restrict__ Kb, const bf16_t* __restrict__ Vt,
;                                           int b, int h, int qb, int lgS, float lam, float oscale, const float* __restrict__ subg, float* stash) {
;     ...
;             for (int r = 0; r < 16; ++r) negm[r] = -mx;
;             float sum = 0.f;
; #pragma unroll
;             for (int r = 0; r < 16; ++r) { p0[r] = __builtin_amdgcn_exp2f(p0[r] - mx); p1[r] = __builtin_amdgcn_exp2f(p1[r] - mx); sum += p0[r] + p1[r]; }
;             lrun = sum;
; #pragma unroll
;             for (int j = 0; j < 8; ++j) { pk[j >> 2][j & 3] = cvtpk_s(p0[2 * j], p0[2 * j + 1]); pk[2 + (j >> 2)][j & 3] = cvtpk_s(p1[2 * j], p1[2 * j + 1]); }
;     ...
;         for (int t = 0; t < NT - 1; ++t) {
;             if (t + 3 < NT) *(LAS u32x4*)(lds + kq0 + kw) = kreg;
;             if (t + 2 < NT) { *(LAS u32x4*)(lds + vs2 + vw0) = vreg0; *(LAS u32x4*)(lds + vs2 + vw1) = vreg1; }
;             if (t + 4 < NT) kreg = *(const GAS u32x4*)(kg + (size_t)(t + 4) * 64 * 512);
;             if (t + 3 < NT) { vreg0 = *(const GAS u32x4*)(vg0 + (t + 3) * 64); vreg1 = *(const GAS u32x4*)(vg1 + (t + 3) * 64); }
;             f32x16 p0, p1;
;             ATT_KRD(kq1, 1, 4);
;             ATT_SB();
;             __builtin_amdgcn_s_setprio(1);
;             ATT_QK(p0, p1);
	v_add_f32_e32 v8, v28, v32
	v_add_f32_e32 v1, v8, v1
	v_add_f32_e32 v8, v29, v33
	v_sub_f32_e32 v24, v24, v250
	v_sub_f32_e32 v46, v25, v250
	v_add_f32_e32 v1, v8, v1
	v_add_f32_e32 v8, v30, v34
	v_exp_f32_e32 v25, v24
	v_exp_f32_e32 v24, v46
	v_exp_f32_e32 v7, v6
	v_sub_f32_e32 v6, v9, v250
	v_add_f32_e32 v1, v8, v1
	v_pk_mov_b32 v[8:9], v[22:23], v[22:23] op_sel:[1,0]
	v_exp_f32_e32 v6, v6
	v_cvt_pk_bf16_f32 v174, v8, v9
	v_pk_mov_b32 v[8:9], v[26:27], v[26:27] op_sel:[1,0]
	v_sub_f32_e32 v39, v16, v250
	v_cvt_pk_bf16_f32 v202, v8, v9
	v_pk_add_f32 v[8:9], v[22:23], v[26:27]
	v_sub_f32_e32 v40, v17, v250
	v_add_f32_e32 v1, v9, v1
	v_add_f32_e32 v1, v8, v1
	v_pk_mov_b32 v[8:9], v[24:25], v[24:25] op_sel:[1,0]
	v_exp_f32_e32 v17, v35
	v_cvt_pk_bf16_f32 v175, v8, v9
	v_pk_mov_b32 v[8:9], v[6:7], v[6:7] op_sel:[1,0]
	v_pk_add_f32 v[6:7], v[24:25], v[6:7]
	v_exp_f32_e32 v16, v36
	v_add_f32_e32 v1, v7, v1
	v_add_f32_e32 v1, v6, v1
	v_pk_mov_b32 v[6:7], v[2:3], v[2:3] op_sel:[1,0]
	v_pk_add_f32 v[2:3], v[2:3], v[14:15]
	v_exp_f32_e32 v19, v37
	v_add_f32_e32 v1, v3, v1
	v_add_f32_e32 v1, v2, v1
	v_pk_mov_b32 v[2:3], v[4:5], v[4:5] op_sel:[1,0]
	v_exp_f32_e32 v18, v38
	v_cvt_pk_bf16_f32 v165, v2, v3
	v_pk_mov_b32 v[2:3], v[16:17], v[16:17] op_sel:[1,0]
	v_exp_f32_e32 v21, v39
	v_cvt_pk_bf16_f32 v181, v2, v3
	v_pk_add_f32 v[2:3], v[4:5], v[16:17]
	v_exp_f32_e32 v20, v40
	v_add_f32_e32 v1, v3, v1
	v_add_f32_e32 v1, v2, v1
	v_pk_mov_b32 v[2:3], v[10:11], v[10:11] op_sel:[1,0]
	v_xor_b32_e32 v64, 0x80000000, v250
	v_cvt_pk_bf16_f32 v166, v2, v3
	v_pk_mov_b32 v[2:3], v[18:19], v[18:19] op_sel:[1,0]
	v_cvt_pk_bf16_f32 v164, v6, v7
	v_cvt_pk_bf16_f32 v182, v2, v3
	v_pk_add_f32 v[2:3], v[10:11], v[18:19]
	v_pk_mov_b32 v[6:7], v[14:15], v[14:15] op_sel:[1,0]
	v_add_f32_e32 v1, v3, v1
	v_add_f32_e32 v1, v2, v1
	v_pk_mov_b32 v[2:3], v[12:13], v[12:13] op_sel:[1,0]
	v_cvt_pk_bf16_f32 v173, v29, v30
	v_cvt_pk_bf16_f32 v167, v2, v3
	v_pk_mov_b32 v[2:3], v[20:21], v[20:21] op_sel:[1,0]
	v_cvt_pk_bf16_f32 v200, v31, v32
	v_cvt_pk_bf16_f32 v183, v2, v3
	v_pk_add_f32 v[2:3], v[12:13], v[20:21]
	v_cvt_pk_bf16_f32 v201, v33, v34
	v_add_f32_e32 v1, v3, v1
	v_cvt_pk_bf16_f32 v203, v8, v9
	v_cvt_pk_bf16_f32 v180, v6, v7
	v_add_f32_e32 v249, v2, v1
	v_mov_b32_e32 v1, v0
	v_mov_b32_e32 v2, v0
	v_mov_b32_e32 v3, v0
	v_mov_b32_e32 v4, v0
	v_mov_b32_e32 v5, v0
	v_mov_b32_e32 v6, v0
	v_mov_b32_e32 v7, v0
	v_mov_b32_e32 v8, v0
	v_mov_b32_e32 v9, v0
	v_mov_b32_e32 v10, v0
	v_mov_b32_e32 v11, v0
	v_mov_b32_e32 v12, v0
	v_mov_b32_e32 v13, v0
	v_mov_b32_e32 v14, v0
	v_mov_b32_e32 v15, v0
	v_mov_b32_e32 v48, v0
	v_mov_b32_e32 v49, v0
	v_mov_b32_e32 v50, v0
	v_mov_b32_e32 v32, v0
	v_mov_b32_e32 v33, v0
	v_mov_b32_e32 v34, v0
	v_mov_b32_e32 v35, v0
	v_mov_b32_e32 v36, v0
	v_mov_b32_e32 v37, v0
	v_mov_b32_e32 v38, v0
	v_mov_b32_e32 v39, v0
	v_mov_b32_e32 v40, v0
	v_mov_b32_e32 v41, v0
	v_mov_b32_e32 v42, v0
	v_mov_b32_e32 v43, v0
	v_mov_b32_e32 v44, v0
	v_mov_b32_e32 v45, v0
	v_mov_b32_e32 v46, v0
	v_mov_b32_e32 v47, v0
	v_mov_b32_e32 v16, v0
	v_mov_b32_e32 v17, v0
	v_mov_b32_e32 v18, v0
	v_mov_b32_e32 v19, v0
	v_mov_b32_e32 v20, v0
	v_mov_b32_e32 v21, v0
	v_mov_b32_e32 v22, v0
	v_mov_b32_e32 v23, v0
	v_mov_b32_e32 v24, v0
	v_mov_b32_e32 v25, v0
	v_mov_b32_e32 v26, v0
	v_mov_b32_e32 v27, v0
	v_mov_b32_e32 v28, v0
	v_mov_b32_e32 v29, v0
	v_mov_b32_e32 v30, v0
	v_mov_b32_e32 v31, v0
	v_mov_b32_e32 v65, v64
	v_mov_b32_e32 v66, v64
	v_mov_b32_e32 v67, v64
	v_mov_b32_e32 v68, v64
	v_mov_b32_e32 v69, v64
	v_mov_b32_e32 v70, v64
	v_mov_b32_e32 v71, v64
	v_mov_b32_e32 v72, v64
	v_mov_b32_e32 v73, v64
	v_mov_b32_e32 v74, v64
	v_mov_b32_e32 v75, v64
	v_mov_b32_e32 v76, v64
	v_mov_b32_e32 v77, v64
	v_mov_b32_e32 v78, v64
	v_mov_b32_e32 v79, v64
.LBB0_335:
	s_mov_b32 s61, s50
	s_mov_b32 s50, s29
	s_mov_b32 s65, s28
	s_setprio 1
	v_mfma_f32_32x32x16_bf16 v[96:111], v[156:159], v[136:139], v[64:79]
	v_mfma_f32_32x32x16_bf16 v[80:95], v[160:163], v[136:139], v[64:79]
	s_setprio 0
	s_add_i32 s29, s57, 3
	s_cmp_lt_u32 s29, s38
	s_cselect_b64 s[30:31], -1, 0
	s_cmp_ge_u32 s29, s38
	s_cbranch_scc1 .Lmy_skip_kw
	v_add_u32_e32 v156, s60, v248
	s_waitcnt vmcnt(0)
	ds_write_b128 v156, v[152:155]
.Lmy_skip_kw:
	v_mfma_f32_32x32x16_bf16 v[96:111], v[204:207], v[140:143], v[96:111]
	s_add_i32 s40, s57, 2
	s_cmp_lt_u32 s40, s38
	s_cselect_b64 s[28:29], -1, 0
	s_cmp_ge_u32 s40, s38
	s_cbranch_scc1 .Lmy_skip_vw
	v_add_u32_e32 v156, s56, v234
	s_waitcnt vmcnt(1)
	ds_write_b128 v156, v[168:171] offset:25344
	s_waitcnt vmcnt(0)
	ds_write_b128 v156, v[176:179] offset:34560
.Lmy_skip_vw:
	v_mfma_f32_32x32x16_bf16 v[80:95], v[208:211], v[140:143], v[80:95]
	s_add_i32 s40, s57, 4
	s_cmp_ge_u32 s40, s38
	s_cbranch_scc1 .Lmy_skip_kl
	global_load_dwordx4 v[152:155], v[238:239], off
.Lmy_skip_kl:
	v_mfma_f32_32x32x16_bf16 v[96:111], v[212:215], v[144:147], v[96:111]
	s_andn2_b64 vcc, exec, s[30:31]
	s_cbranch_vccnz .Lmy_skip_vl
	s_lshl_b64 s[30:31], s[90:91], 1
	v_lshl_add_u64 v[156:157], v[230:231], 0, s[30:31]
	v_lshl_add_u64 v[158:159], v[232:233], 0, s[30:31]
	global_load_dwordx4 v[168:171], v[156:157], off
	global_load_dwordx4 v[176:179], v[158:159], off
; __device__ __forceinline__ void attn_unit(LAS unsigned char* lds, bf16_t* Qm, const bf16_t* __restrict__ Kb, const bf16_t* __restrict__ Vt,
;                                           int b, int h, int qb, int lgS, float lam, float oscale, const float* __restrict__ subg, float* stash) {
;     ...
;             ATT_QK(p0, p1);
;             __builtin_amdgcn_s_setprio(0);
;             ATT_SB();
; #pragma unroll
;             for (int b2 = 0; b2 < 4; ++b2) vfb[b2] = *(const LAS bf16x8*)(lds + vs0 + vr + b2 * 32 * VP + 32);
;             float mxa, mxb;
;             o[0] = __builtin_amdgcn_mfma_f32_32x32x16_bf16(vfa[0], __builtin_bit_cast(bf16x8, pk[0]), o[0], 0, 0, 0);
;             mxa = ATT_MX3(p0[0], p0[1], p1[0]); mxb = ATT_MX3(p0[2], p0[3], p1[1]); mxa = ATT_MX3(mxa, p1[2], p1[3]); mxa = ATT_MX3(mxa, p0[4], p0[5]); mxb = ATT_MX3(mxb, p0[6], p0[7]);
;             ATT_SB();
;             o[1] = __builtin_amdgcn_mfma_f32_32x32x16_bf16(vfa[1], __builtin_bit_cast(bf16x8, pk[0]), o[1], 0, 0, 0);
;             mxa = ATT_MX3(mxa, p1[4], p1[5]); mxb = ATT_MX3(mxb, p1[6], p1[7]); mxa = ATT_MX3(mxa, p0[8], p0[9]); mxb = ATT_MX3(mxb, p0[10], p0[11]); mxa = ATT_MX3(mxa, p1[8], p1[9]);
;             ATT_SB();
;             o[2] = __builtin_amdgcn_mfma_f32_32x32x16_bf16(vfa[2], __builtin_bit_cast(bf16x8, pk[0]), o[2], 0, 0, 0);
;             mxb = ATT_MX3(mxb, p1[10], p1[11]); mxa = ATT_MX3(mxa, p0[12], p0[13]); mxb = ATT_MX3(mxb, p0[14], p0[15]); mxa = ATT_MX3(mxa, p1[12], p1[13]); mxb = ATT_MX3(mxb, p1[14], p1[15]);
;             ATT_SB();
;             o[3] = __builtin_amdgcn_mfma_f32_32x32x16_bf16(vfa[3], __builtin_bit_cast(bf16x8, pk[0]), o[3], 0, 0, 0);
;             float mx;
;             { const float m_ = __builtin_fmaxf(mxa, mxb); auto rr_ = __builtin_amdgcn_permlane32_swap(__float_as_uint(m_), __float_as_uint(m_), false, false);
;               mx = __builtin_fmaxf(__uint_as_float(rr_[0]), __uint_as_float(rr_[1])); }
;             ATT_SB();
;             if (__builtin_expect(__any(mx > 8.0f), 0)) {
;                 const float dl = (mx > 8.0f) ? mx : 0.f;
;                 mhat += dl;
; #pragma unroll
;                 for (int r = 0; r < 16; ++r) { p0[r] -= dl; p1[r] -= dl; }
;                 const float f = __builtin_amdgcn_exp2f(-dl);
;                 lrun *= f;
; #pragma unroll
;                 for (int i = 0; i < 4; ++i) o[i] = o[i] * f;
; #pragma unroll
.Lmy_skip_vl:
	v_mfma_f32_32x32x16_bf16 v[80:95], v[216:219], v[144:147], v[80:95]
	v_add_u32_e32 v251, s65, v220
	ds_read_b128 v[216:219], v251 offset:25376
	ds_read_b128 v[212:215], v251 offset:29984
	ds_read_b128 v[208:211], v251 offset:34592
	ds_read_b128 v[204:207], v251 offset:39200
	v_mfma_f32_32x32x16_bf16 v[96:111], v[222:225], v[148:151], v[96:111]
	v_mfma_f32_32x32x16_bf16 v[80:95], v[240:243], v[148:151], v[80:95]
	s_nop 10
	v_max_f32_e32 v222, v96, v97
	v_mfma_f32_32x32x16_bf16 v[0:15], v[196:199], v[200:203], v[0:15]
	v_max3_f32 v223, v98, v99, v81
	v_max3_f32 v222, v222, v80, v82
	v_max3_f32 v222, v222, v83, v100
	v_max3_f32 v223, v223, v102, v103
	v_mfma_f32_32x32x16_bf16 v[48:63], v[192:195], v[200:203], v[48:63]
	v_max3_f32 v192, v222, v101, v84
	v_max3_f32 v193, v223, v86, v87
	v_max3_f32 v192, v192, v85, v104
	v_max3_f32 v193, v193, v106, v107
	v_max3_f32 v192, v192, v105, v88
	v_mfma_f32_32x32x16_bf16 v[32:47], v[188:191], v[200:203], v[32:47]
	v_max3_f32 v188, v193, v90, v91
	v_max3_f32 v189, v192, v89, v108
	v_max3_f32 v188, v188, v110, v111
	v_max3_f32 v189, v189, v109, v92
	v_max3_f32 v188, v188, v94, v95
	v_mfma_f32_32x32x16_bf16 v[16:31], v[184:187], v[200:203], v[16:31]
	v_max3_f32 v184, v189, v93, v188
	v_mov_b32_e32 v185, v184
	s_nop 1
	v_permlane32_swap_b32_e32 v184, v185
	v_max_f32_e32 v184, v184, v185
	s_mov_b32 s30, 0x41000000
	v_cmp_lt_f32_e32 vcc, s30, v184
	s_cbranch_vccnz .LBB0_348
.LBB0_342:
	v_exp_f32_e32 v96, v96
	s_waitcnt lgkmcnt(3)
	v_mfma_f32_32x32x16_bf16 v[0:15], v[216:219], v[180:183], v[0:15]
	v_exp_f32_e32 v97, v97
	ds_read_b128 v[192:195], v251 offset:25408
	ds_read_b128 v[196:199], v251 offset:30016
	ds_read_b128 v[188:191], v251 offset:34624
	ds_read_b128 v[184:187], v251 offset:39232
	v_exp_f32_e32 v88, v88
	v_add_f32_e32 v200, 0, v96
	v_exp_f32_e32 v89, v89
	v_add_f32_e32 v200, v97, v200
	s_nop 0
	v_add_f32_e32 v200, v88, v200
	v_add_f32_e32 v200, v89, v200
	v_exp_f32_e32 v98, v98
	s_waitcnt lgkmcnt(6)
	v_mfma_f32_32x32x16_bf16 v[48:63], v[212:215], v[180:183], v[48:63]
	v_exp_f32_e32 v99, v99
	v_exp_f32_e32 v90, v90
	v_add_f32_e32 v200, v98, v200
	v_exp_f32_e32 v91, v91
	v_add_f32_e32 v200, v99, v200
	s_nop 0
	v_add_f32_e32 v200, v90, v200
	v_add_f32_e32 v200, v91, v200
	v_exp_f32_e32 v100, v100
	s_waitcnt lgkmcnt(5)
	v_mfma_f32_32x32x16_bf16 v[32:47], v[208:211], v[180:183], v[32:47]
	v_exp_f32_e32 v101, v101
	v_exp_f32_e32 v92, v92
	v_add_f32_e32 v200, v100, v200
	v_exp_f32_e32 v93, v93
	v_add_f32_e32 v200, v101, v200
	s_nop 0
	v_add_f32_e32 v200, v92, v200
	v_add_f32_e32 v200, v93, v200
	v_exp_f32_e32 v102, v102
	s_waitcnt lgkmcnt(4)
	v_mfma_f32_32x32x16_bf16 v[16:31], v[204:207], v[180:183], v[16:31]
	v_exp_f32_e32 v103, v103
	v_exp_f32_e32 v94, v94
	v_add_f32_e32 v180, v102, v200
	v_exp_f32_e32 v95, v95
	v_add_f32_e32 v180, v103, v180
	s_nop 0
	v_add_f32_e32 v180, v94, v180
	v_add_f32_e32 v212, v95, v180
	s_waitcnt lgkmcnt(3)
	v_mfma_f32_32x32x16_bf16 v[0:15], v[192:195], v[172:175], v[0:15]
	ds_read_b128 v[180:183], v251 offset:25440
	ds_read_b128 v[200:203], v251 offset:30048
	ds_read_b128 v[204:207], v251 offset:34656
	ds_read_b128 v[208:211], v251 offset:39264
	v_exp_f32_e32 v104, v104
	v_exp_f32_e32 v105, v105
	v_add_f32_e32 v156, v104, v212
	v_add_f32_e32 v156, v105, v156
	v_add_u32_e32 v251, s25, v220
	v_add_u32_e32 v160, s50, v235
	s_waitcnt lgkmcnt(6)
	v_mfma_f32_32x32x16_bf16 v[48:63], v[196:199], v[172:175], v[48:63]
	ds_read_b128 v[192:195], v251 offset:29952
	v_exp_f32_e32 v106, v106
	v_exp_f32_e32 v107, v107
	v_add_f32_e32 v156, v106, v156
	v_add_f32_e32 v156, v107, v156
	s_cmp_eq_u32 s98, 0
	s_cbranch_scc1 .Lmy_skip_m
	s_waitcnt lgkmcnt(1)
	s_barrier
.Lmy_skip_m:
	s_waitcnt lgkmcnt(6)
	v_mfma_f32_32x32x16_bf16 v[32:47], v[188:191], v[172:175], v[32:47]
	ds_read_b128 v[196:199], v251 offset:25344
	v_exp_f32_e32 v108, v108
	v_exp_f32_e32 v109, v109
	v_add_f32_e32 v156, v108, v156
	v_add_f32_e32 v156, v109, v156
	s_waitcnt lgkmcnt(6)
	v_mfma_f32_32x32x16_bf16 v[16:31], v[184:187], v[172:175], v[16:31]
	ds_read_b128 v[188:191], v251 offset:34560
	ds_read_b128 v[212:215], v160 offset:4224
	ds_read_b128 v[216:219], v160 offset:4736
	v_exp_f32_e32 v110, v110
	v_exp_f32_e32 v111, v111
	v_add_f32_e32 v156, v110, v156
	v_add_f32_e32 v156, v111, v156
	s_waitcnt lgkmcnt(8)
	v_mfma_f32_32x32x16_bf16 v[0:15], v[180:183], v[164:167], v[0:15]
	ds_read_b128 v[184:187], v251 offset:39168
	ds_read_b128 v[222:225], v160 offset:6336
	ds_read_b128 v[240:243], v160 offset:6848
	v_exp_f32_e32 v80, v80
	v_exp_f32_e32 v81, v81
	v_add_f32_e32 v156, v80, v156
	v_add_f32_e32 v156, v81, v156
	v_cvt_pk_bf16_f32 v180, v104, v105
	v_cvt_pk_bf16_f32 v181, v106, v107
	v_cvt_pk_bf16_f32 v182, v108, v109
	v_cvt_pk_bf16_f32 v183, v110, v111
	s_waitcnt lgkmcnt(10)
	v_mfma_f32_32x32x16_bf16 v[48:63], v[200:203], v[164:167], v[48:63]
	v_exp_f32_e32 v82, v82
	v_exp_f32_e32 v83, v83
	v_add_f32_e32 v156, v82, v156
	v_add_f32_e32 v156, v83, v156
	v_cvt_pk_bf16_f32 v200, v96, v97
	v_cvt_pk_bf16_f32 v201, v98, v99
	v_cvt_pk_bf16_f32 v202, v100, v101
	v_cvt_pk_bf16_f32 v203, v102, v103
	v_cvt_pk_bf16_f32 v172, v80, v81
	s_waitcnt lgkmcnt(9)
	v_mfma_f32_32x32x16_bf16 v[32:47], v[204:207], v[164:167], v[32:47]
	ds_read_b128 v[204:207], v160 offset:2112
	v_exp_f32_e32 v84, v84
	v_exp_f32_e32 v85, v85
	v_add_f32_e32 v156, v84, v156
	v_add_f32_e32 v156, v85, v156
	v_cvt_pk_bf16_f32 v173, v82, v83
	s_waitcnt lgkmcnt(9)
	v_mfma_f32_32x32x16_bf16 v[16:31], v[208:211], v[164:167], v[16:31]
	ds_read_b128 v[208:211], v160 offset:2624
	v_exp_f32_e32 v86, v86
	v_exp_f32_e32 v87, v87
	v_add_f32_e32 v156, v86, v156
	v_add_f32_e32 v156, v87, v156
	v_add_f32_e32 v249, v249, v156
	ds_read_b128 v[156:159], v160
	ds_read_b128 v[160:163], v160 offset:512
	v_cvt_pk_bf16_f32 v174, v84, v85
	v_cvt_pk_bf16_f32 v175, v86, v87
	v_cvt_pk_bf16_f32 v164, v88, v89
	v_cvt_pk_bf16_f32 v165, v90, v91
	v_cvt_pk_bf16_f32 v166, v92, v93
	v_cvt_pk_bf16_f32 v167, v94, v95
	s_add_i32 s57, s57, 1
	s_add_i32 s90, s90, 64
	s_mov_b64 s[28:29], 0x10000
	v_lshl_add_u64 v[238:239], v[238:239], 0, s[28:29]
	s_waitcnt lgkmcnt(0)
	s_cmp_lg_u32 s98, 0
	s_cbranch_scc1 .Lmy_skip_e
	s_barrier
.Lmy_skip_e:
	s_cmp_eq_u32 s63, s57
	s_cbranch_scc1 .LBB0_349
	s_mov_b32 s28, s25
	s_mov_b32 s25, s56
	s_mov_b32 s29, s60
	s_mov_b32 s60, s61
	s_mov_b32 s56, s65
	s_branch .LBB0_335

; __global__ void __launch_bounds__(512, 2) fwd_megakernel(mk::Params p) {
	.amdhsa_kernel _Z14fwd_megakernelN2mk6ParamsE
		.amdhsa_group_segment_fixed_size 0
		.amdhsa_private_segment_fixed_size 0
		.amdhsa_kernarg_size 408
		.amdhsa_user_sgpr_count 2
		.amdhsa_user_sgpr_dispatch_ptr 0
		.amdhsa_user_sgpr_queue_ptr 0
		.amdhsa_user_sgpr_kernarg_segment_ptr 1
		.amdhsa_user_sgpr_dispatch_id 0
		.amdhsa_user_sgpr_kernarg_preload_length 0
		.amdhsa_user_sgpr_kernarg_preload_offset 0
		.amdhsa_user_sgpr_private_segment_size 0
		.amdhsa_uses_dynamic_stack 0
		.amdhsa_enable_private_segment 0
		.amdhsa_system_sgpr_workgroup_id_x 1
		.amdhsa_system_sgpr_workgroup_id_y 0
		.amdhsa_system_sgpr_workgroup_id_z 0
		.amdhsa_system_sgpr_workgroup_info 0
		.amdhsa_system_vgpr_workitem_id 2
		.amdhsa_next_free_vgpr 256
		.amdhsa_next_free_sgpr 102
		.amdhsa_accum_offset 256
		.amdhsa_reserve_vcc 1
		.amdhsa_float_round_mode_32 0
		.amdhsa_float_round_mode_16_64 0
		.amdhsa_float_denorm_mode_32 3
		.amdhsa_float_denorm_mode_16_64 3
		.amdhsa_dx10_clamp 1
		.amdhsa_ieee_mode 1
		.amdhsa_fp16_overflow 0
		.amdhsa_tg_split 0
		.amdhsa_exception_fp_ieee_invalid_op 0
		.amdhsa_exception_fp_denorm_src 0
		.amdhsa_exception_fp_ieee_div_zero 0
		.amdhsa_exception_fp_ieee_overflow 0
		.amdhsa_exception_fp_ieee_underflow 0
		.amdhsa_exception_fp_ieee_inexact 0
		.amdhsa_exception_int_div_zero 0
	.end_amdhsa_kernel

; __global__ void __launch_bounds__(512, 2) fwd_megakernel(mk::Params p) {
amdhsa.kernels:
  - .agpr_count:     0
    .args:
      - .offset:         0
        .size:           152
        .value_kind:     by_value
      - .offset:         152
        .size:           4
        .value_kind:     hidden_block_count_x
      - .offset:         156
        .size:           4
        .value_kind:     hidden_block_count_y
      - .offset:         160
        .size:           4
        .value_kind:     hidden_block_count_z
      - .offset:         164
        .size:           2
        .value_kind:     hidden_group_size_x
      - .offset:         166
        .size:           2
        .value_kind:     hidden_group_size_y
      - .offset:         168
        .size:           2
        .value_kind:     hidden_group_size_z
      - .offset:         170
        .size:           2
        .value_kind:     hidden_remainder_x
      - .offset:         172
        .size:           2
        .value_kind:     hidden_remainder_y
      - .offset:         174
        .size:           2
        .value_kind:     hidden_remainder_z
      - .offset:         192
        .size:           8
        .value_kind:     hidden_global_offset_x
      - .offset:         200
        .size:           8
        .value_kind:     hidden_global_offset_y
      - .offset:         208
        .size:           8
        .value_kind:     hidden_global_offset_z
      - .offset:         216
        .size:           2
        .value_kind:     hidden_grid_dims
      - .offset:         240
        .size:           8
        .value_kind:     hidden_multigrid_sync_arg
      - .offset:         272
        .size:           4
        .value_kind:     hidden_dynamic_lds_size
    .group_segment_fixed_size: 0
    .kernarg_segment_align: 8
    .kernarg_segment_size: 408
    .language:       OpenCL C
    .language_version:
      - 2
      - 0
    .max_flat_workgroup_size: 512
    .name:           _Z14fwd_megakernelN2mk6ParamsE
    .private_segment_fixed_size: 0
    .sgpr_count:     108
    .sgpr_spill_count: 62
    .symbol:         _Z14fwd_megakernelN2mk6ParamsE.kd
    .uniform_work_group_size: 1
    .uses_dynamic_stack: false
    .vgpr_count:     256
    .vgpr_spill_count: 0
    .wavefront_size: 64
